# attention K-tile loop rewritten: LDS fragment reads issued ahead of their MFMAs, separate straight-line paths for waves 0-3 / 4-7, exp in place
# speedup vs baseline: 1.0140x; 1.0103x over previous
; #define LAS __attribute__((address_space(3)))
; #define SB0() __builtin_amdgcn_sched_barrier(0)
; template <bool SHIFT> DI void attn_unit(LAS unsigned char* lds, const bf16_t* Qb, const bf16_t* Kb, const bf16_t* Vt, bf16_t* concat,
;                   int b, int h, int qt, float shift2, float lam, int lam_init_bits, const float* subln_g) {
;     ...
;     const bool lag = wid >= 4;
;     bf16x8 Pc[2][2];
; #pragma unroll
;     for (int m = 0; m < 2; ++m)
; #pragma unroll
;         for (int g = 0; g < 2; ++g) { u32x4 z = {0u, 0u, 0u, 0u}; Pc[m][g] = __builtin_bit_cast(bf16x8, z); }
;     const LAS unsigned char* vold = lds + V_OFF + r * VP + hh * 16;
;     int vcur = 0;
;     for (int kt = 0; kt < nkt; ++kt) {
;         const int cur = kt & 1, nx = cur ^ 1;
;         const int vnx = vcur == 2 ? 0 : vcur + 1;
;         const bool pf = (kt + 1 < nkt);
;         const size_t ko = (size_t)(kt + 1) * 64;
;         if (pf) { *(LAS u32x4*)(lds + K_OFF + nx * K_BYTES + krow0 * QP + kc * 16) = sg0; *(LAS u32x4*)(lds + K_OFF + nx * K_BYTES + (krow0 + 32) * QP + kc * 16) = sg1;
;             sg0 = *(const u32x4*)(vg + (size_t)(vrow0) * TPB + ko + vc * 8); sg1 = *(const u32x4*)(vg + (size_t)(vrow0 + 64) * TPB + ko + vc * 8); }
;         const LAS unsigned char* kb = lds + K_OFF + cur * K_BYTES + r * QP + hh * 16;
;         const LAS unsigned char* vb = lds + V_OFF + vcur * V_BYTES + r * VP + hh * 16;
; #pragma unroll
;         for (int half = 0; half < 2; ++half) {
;             if (lag) PVH(Pc, vold);
;             QKEXP(Pc, half);
;             if (half == 0 && pf) { *(LAS u32x4*)(lds + V_OFF + vnx * V_BYTES + vrow0 * VP + vc * 16) = sg0; *(LAS u32x4*)(lds + V_OFF + vnx * V_BYTES + (vrow0 + 64) * VP + vc * 16) = sg1;
;                 if (kt + 2 < nkt) { sg0 = *(const u32x4*)(kg + (ko + 64 + krow0) * 1024 + kc * 8); sg1 = *(const u32x4*)(kg + (ko + 64 + krow0 + 32) * 1024 + kc * 8); } }
;             vold = vb + half * 64;
;             SB0();
;             if (!lag) PVH(Pc, vold);
.LBB0_533:
	s_and_b32 s6, s34, 1
	s_xor_b32 s4, s6, 1
	s_mulk_i32 s4, 0x4400
	s_add_i32 s4, s4, 0x11000
	v_add3_u32 v137, s4, v210, v160
	v_add3_u32 v142, s4, v214, v160
	s_mulk_i32 s6, 0x4400
	v_add_u32_e32 v254, s6, v212
	s_mul_i32 s6, s40, 0x4800
	v_add_u32_e32 v217, s6, v213
	s_add_i32 s7, s40, 1
	s_cmp_lg_u32 s40, 2
	s_cselect_b32 s65, s7, 0
	s_mul_i32 s37, s65, 0x4800
	s_add_i32 s6, s37, 0x19800
	v_add3_u32 v218, s6, v215, v176
	v_add3_u32 v219, s6, v216, v176
	v_add_co_u32_e32 v138, vcc, 0xffef8000, v168
	s_andn2_b64 s[4:5], exec, s[18:19]
	s_andn2_b64 s[6:7], exec, s[20:21]
	v_addc_co_u32_e32 v139, vcc, -1, v169, vcc
	s_waitcnt vmcnt(0)
	ds_write_b128 v137, v[144:147]
	ds_write_b128 v142, v[148:151]
	global_load_dwordx4 v[144:147], v[138:139], off
	global_load_dwordx4 v[148:151], v[168:169], off
	s_and_b64 vcc, exec, s[18:19]
	s_cbranch_vccnz .Lattn_lag
	ds_read_b128 v[178:181], v254
	ds_read_b128 v[194:197], v211
	ds_read_b128 v[182:185], v254 offset:32
	ds_read_b128 v[198:201], v211 offset:32
	ds_read_b128 v[186:189], v254 offset:64
	ds_read_b128 v[202:205], v211 offset:64
	ds_read_b128 v[190:193], v254 offset:96
	ds_read_b128 v[206:209], v211 offset:96
	s_waitcnt lgkmcnt(6)
	v_mfma_f32_32x32x16_bf16 v[238:253], v[178:181], v[194:197], 0
	ds_read_b128 v[178:181], v254 offset:128
	ds_read_b128 v[194:197], v211 offset:128
	s_waitcnt lgkmcnt(6)
	v_mfma_f32_32x32x16_bf16 v[238:253], v[182:185], v[198:201], v[238:253]
	ds_read_b128 v[182:185], v254 offset:160
	ds_read_b128 v[198:201], v211 offset:160
	s_waitcnt lgkmcnt(6)
	v_mfma_f32_32x32x16_bf16 v[238:253], v[186:189], v[202:205], v[238:253]
	ds_read_b128 v[186:189], v254 offset:192
	ds_read_b128 v[202:205], v211 offset:192
	s_waitcnt lgkmcnt(6)
	v_mfma_f32_32x32x16_bf16 v[238:253], v[190:193], v[206:209], v[238:253]
	ds_read_b128 v[190:193], v254 offset:224
	ds_read_b128 v[206:209], v211 offset:224
	s_waitcnt lgkmcnt(6)
	v_mfma_f32_32x32x16_bf16 v[128:143], v[178:181], v[194:197], 0
	s_waitcnt lgkmcnt(4)
	v_mfma_f32_32x32x16_bf16 v[128:143], v[182:185], v[198:201], v[128:143]
	s_waitcnt lgkmcnt(2)
	v_mfma_f32_32x32x16_bf16 v[128:143], v[186:189], v[202:205], v[128:143]
	s_waitcnt lgkmcnt(0)
	v_mfma_f32_32x32x16_bf16 v[128:143], v[190:193], v[206:209], v[128:143]
	ds_read_b128 v[228:231], v217
	ds_read_b128 v[232:235], v217 offset:4608
	s_nop 3
	v_exp_f32_e32 v238, v238
	v_exp_f32_e32 v239, v239
	v_exp_f32_e32 v240, v240
	v_exp_f32_e32 v241, v241
	v_exp_f32_e32 v242, v242
	v_exp_f32_e32 v243, v243
	v_exp_f32_e32 v244, v244
	v_exp_f32_e32 v245, v245
	v_exp_f32_e32 v246, v246
	v_exp_f32_e32 v247, v247
	v_exp_f32_e32 v248, v248
	v_exp_f32_e32 v249, v249
	v_exp_f32_e32 v250, v250
	v_exp_f32_e32 v251, v251
	v_exp_f32_e32 v252, v252
	v_exp_f32_e32 v253, v253
	v_add_f32_e32 v174, v238, v239
	v_add_f32_e32 v175, v240, v241
	v_add_f32_e32 v174, v174, v242
	v_add_f32_e32 v175, v175, v243
	v_add_f32_e32 v174, v174, v244
	v_add_f32_e32 v175, v175, v245
	v_add_f32_e32 v174, v174, v246
	v_add_f32_e32 v175, v175, v247
	v_add_f32_e32 v174, v174, v248
	v_add_f32_e32 v175, v175, v249
	v_add_f32_e32 v174, v174, v250
	v_add_f32_e32 v175, v175, v251
	v_add_f32_e32 v174, v174, v252
	v_add_f32_e32 v175, v175, v253
	v_add_f32_e32 v174, v174, v175
	v_add_f32_e32 v165, v165, v174
	v_cvt_pk_bf16_f32 v156, v238, v239
	v_cvt_pk_bf16_f32 v157, v240, v241
	v_cvt_pk_bf16_f32 v158, v242, v243
	v_cvt_pk_bf16_f32 v159, v244, v245
	v_cvt_pk_bf16_f32 v152, v246, v247
	v_cvt_pk_bf16_f32 v153, v248, v249
	v_cvt_pk_bf16_f32 v154, v250, v251
	v_cvt_pk_bf16_f32 v155, v252, v253
	v_exp_f32_e32 v128, v128
	v_exp_f32_e32 v129, v129
	v_exp_f32_e32 v130, v130
	v_exp_f32_e32 v131, v131
	v_exp_f32_e32 v132, v132
	v_exp_f32_e32 v133, v133
	v_exp_f32_e32 v134, v134
	v_exp_f32_e32 v135, v135
	v_exp_f32_e32 v136, v136
	v_exp_f32_e32 v137, v137
	v_exp_f32_e32 v138, v138
	v_exp_f32_e32 v139, v139
	v_exp_f32_e32 v140, v140
	v_exp_f32_e32 v141, v141
	v_exp_f32_e32 v142, v142
	v_exp_f32_e32 v143, v143
	v_add_f32_e32 v174, v128, v129
	v_add_f32_e32 v175, v130, v131
	v_add_f32_e32 v174, v174, v132
	v_add_f32_e32 v175, v175, v133
	v_add_f32_e32 v174, v174, v134
	v_add_f32_e32 v175, v175, v135
	v_add_f32_e32 v174, v174, v136
	v_add_f32_e32 v175, v175, v137
	v_add_f32_e32 v174, v174, v138
	v_add_f32_e32 v175, v175, v139
	v_add_f32_e32 v174, v174, v140
	v_add_f32_e32 v175, v175, v141
	v_add_f32_e32 v174, v174, v142
	v_add_f32_e32 v175, v175, v143
	v_add_f32_e32 v174, v174, v175
	v_add_f32_e32 v164, v164, v174
	v_cvt_pk_bf16_f32 v135, v134, v135
	v_cvt_pk_bf16_f32 v134, v132, v133
	v_cvt_pk_bf16_f32 v133, v130, v131
	v_cvt_pk_bf16_f32 v132, v128, v129
	v_cvt_pk_bf16_f32 v128, v136, v137
	v_cvt_pk_bf16_f32 v129, v138, v139
	v_cvt_pk_bf16_f32 v130, v140, v141
	v_cvt_pk_bf16_f32 v131, v142, v143
	s_nop 1
	s_waitcnt vmcnt(0)
	ds_write_b128 v218, v[144:147]
	ds_write_b128 v219, v[148:151]
	s_cmp_ge_u32 s34, s35
	s_cbranch_scc1 .Lattn_kskip_n
	v_lshl_add_u64 v[170:171], v[166:167], 0, s[22:23]
	v_add_co_u32_e32 v172, vcc, 0xc5c8000, v170
	s_nop 1
	v_addc_co_u32_e32 v173, vcc, 0, v171, vcc
	v_add_co_u32_e32 v170, vcc, 0xc5d8000, v170
	s_nop 1
	v_addc_co_u32_e32 v171, vcc, 0, v171, vcc
	global_load_dwordx4 v[144:147], v[172:173], off
	global_load_dwordx4 v[148:151], v[170:171], off
; #define LAS __attribute__((address_space(3)))
; #define SB0() __builtin_amdgcn_sched_barrier(0)
; template <bool SHIFT> DI void attn_unit(LAS unsigned char* lds, const bf16_t* Qb, const bf16_t* Kb, const bf16_t* Vt, bf16_t* concat,
;                   int b, int h, int qt, float shift2, float lam, int lam_init_bits, const float* subln_g) {
;     ...
;     const bool lag = wid >= 4;
;     bf16x8 Pc[2][2];
; #pragma unroll
;     for (int m = 0; m < 2; ++m)
; #pragma unroll
;         for (int g = 0; g < 2; ++g) { u32x4 z = {0u, 0u, 0u, 0u}; Pc[m][g] = __builtin_bit_cast(bf16x8, z); }
;     const LAS unsigned char* vold = lds + V_OFF + r * VP + hh * 16;
;     int vcur = 0;
;     for (int kt = 0; kt < nkt; ++kt) {
;         const int cur = kt & 1, nx = cur ^ 1;
;         const int vnx = vcur == 2 ? 0 : vcur + 1;
;         const bool pf = (kt + 1 < nkt);
;         const size_t ko = (size_t)(kt + 1) * 64;
;         if (pf) { *(LAS u32x4*)(lds + K_OFF + nx * K_BYTES + krow0 * QP + kc * 16) = sg0; *(LAS u32x4*)(lds + K_OFF + nx * K_BYTES + (krow0 + 32) * QP + kc * 16) = sg1;
;             sg0 = *(const u32x4*)(vg + (size_t)(vrow0) * TPB + ko + vc * 8); sg1 = *(const u32x4*)(vg + (size_t)(vrow0 + 64) * TPB + ko + vc * 8); }
;         const LAS unsigned char* kb = lds + K_OFF + cur * K_BYTES + r * QP + hh * 16;
;         const LAS unsigned char* vb = lds + V_OFF + vcur * V_BYTES + r * VP + hh * 16;
; #pragma unroll
;         for (int half = 0; half < 2; ++half) {
;             if (lag) PVH(Pc, vold);
;             QKEXP(Pc, half);
;             if (half == 0 && pf) { *(LAS u32x4*)(lds + V_OFF + vnx * V_BYTES + vrow0 * VP + vc * 16) = sg0; *(LAS u32x4*)(lds + V_OFF + vnx * V_BYTES + (vrow0 + 64) * VP + vc * 16) = sg1;
;                 if (kt + 2 < nkt) { sg0 = *(const u32x4*)(kg + (ko + 64 + krow0) * 1024 + kc * 8); sg1 = *(const u32x4*)(kg + (ko + 64 + krow0 + 32) * 1024 + kc * 8); } }
;             vold = vb + half * 64;
;             SB0();
;             if (!lag) PVH(Pc, vold);
.Lattn_kskip_n:
	s_waitcnt lgkmcnt(3)
	v_mfma_f32_32x32x16_bf16 v[112:127], v[228:231], v[156:159], v[112:127]
	v_mfma_f32_32x32x16_bf16 v[96:111], v[228:231], v[132:135], v[96:111]
	ds_read_b128 v[228:231], v217 offset:9216
	s_waitcnt lgkmcnt(3)
	v_mfma_f32_32x32x16_bf16 v[80:95], v[232:235], v[156:159], v[80:95]
	v_mfma_f32_32x32x16_bf16 v[64:79], v[232:235], v[132:135], v[64:79]
	ds_read_b128 v[232:235], v217 offset:13824
	s_waitcnt lgkmcnt(1)
	v_mfma_f32_32x32x16_bf16 v[32:47], v[228:231], v[156:159], v[32:47]
	v_mfma_f32_32x32x16_bf16 v[48:63], v[228:231], v[132:135], v[48:63]
	ds_read_b128 v[228:231], v217 offset:32
	s_waitcnt lgkmcnt(1)
	v_mfma_f32_32x32x16_bf16 v[16:31], v[232:235], v[156:159], v[16:31]
	v_mfma_f32_32x32x16_bf16 v[0:15], v[232:235], v[132:135], v[0:15]
	ds_read_b128 v[232:235], v217 offset:4640
	s_waitcnt lgkmcnt(1)
	v_mfma_f32_32x32x16_bf16 v[112:127], v[228:231], v[152:155], v[112:127]
	v_mfma_f32_32x32x16_bf16 v[96:111], v[228:231], v[128:131], v[96:111]
	ds_read_b128 v[228:231], v217 offset:9248
	s_waitcnt lgkmcnt(1)
	v_mfma_f32_32x32x16_bf16 v[80:95], v[232:235], v[152:155], v[80:95]
	v_mfma_f32_32x32x16_bf16 v[64:79], v[232:235], v[128:131], v[64:79]
	ds_read_b128 v[232:235], v217 offset:13856
	ds_read_b128 v[178:181], v254 offset:8704
	ds_read_b128 v[194:197], v211
	ds_read_b128 v[182:185], v254 offset:8736
	ds_read_b128 v[198:201], v211 offset:32
	ds_read_b128 v[186:189], v254 offset:8768
	ds_read_b128 v[202:205], v211 offset:64
	ds_read_b128 v[190:193], v254 offset:8800
	ds_read_b128 v[206:209], v211 offset:96
	s_waitcnt lgkmcnt(9)
	v_mfma_f32_32x32x16_bf16 v[32:47], v[228:231], v[152:155], v[32:47]
	v_mfma_f32_32x32x16_bf16 v[48:63], v[228:231], v[128:131], v[48:63]
	s_waitcnt lgkmcnt(8)
	v_mfma_f32_32x32x16_bf16 v[16:31], v[232:235], v[152:155], v[16:31]
	v_mfma_f32_32x32x16_bf16 v[0:15], v[232:235], v[128:131], v[0:15]
	s_waitcnt lgkmcnt(6)
	v_mfma_f32_32x32x16_bf16 v[238:253], v[178:181], v[194:197], 0
	ds_read_b128 v[178:181], v254 offset:8832
	ds_read_b128 v[194:197], v211 offset:128
	s_waitcnt lgkmcnt(6)
	v_mfma_f32_32x32x16_bf16 v[238:253], v[182:185], v[198:201], v[238:253]
	ds_read_b128 v[182:185], v254 offset:8864
	ds_read_b128 v[198:201], v211 offset:160
	s_waitcnt lgkmcnt(6)
	v_mfma_f32_32x32x16_bf16 v[238:253], v[186:189], v[202:205], v[238:253]
	ds_read_b128 v[186:189], v254 offset:8896
	ds_read_b128 v[202:205], v211 offset:192
	s_waitcnt lgkmcnt(6)
	v_mfma_f32_32x32x16_bf16 v[238:253], v[190:193], v[206:209], v[238:253]
	ds_read_b128 v[190:193], v254 offset:8928
	ds_read_b128 v[206:209], v211 offset:224
	s_waitcnt lgkmcnt(6)
	v_mfma_f32_32x32x16_bf16 v[128:143], v[178:181], v[194:197], 0
	s_waitcnt lgkmcnt(4)
	v_mfma_f32_32x32x16_bf16 v[128:143], v[182:185], v[198:201], v[128:143]
	s_waitcnt lgkmcnt(2)
	v_mfma_f32_32x32x16_bf16 v[128:143], v[186:189], v[202:205], v[128:143]
	s_waitcnt lgkmcnt(0)
	v_mfma_f32_32x32x16_bf16 v[128:143], v[190:193], v[206:209], v[128:143]
	ds_read_b128 v[228:231], v217 offset:64
	ds_read_b128 v[232:235], v217 offset:4672
	s_nop 3
	v_exp_f32_e32 v238, v238
	v_exp_f32_e32 v239, v239
	v_exp_f32_e32 v240, v240
	v_exp_f32_e32 v241, v241
	v_exp_f32_e32 v242, v242
	v_exp_f32_e32 v243, v243
	v_exp_f32_e32 v244, v244
	v_exp_f32_e32 v245, v245
	v_exp_f32_e32 v246, v246
	v_exp_f32_e32 v247, v247
	v_exp_f32_e32 v248, v248
	v_exp_f32_e32 v249, v249
	v_exp_f32_e32 v250, v250
	v_exp_f32_e32 v251, v251
	v_exp_f32_e32 v252, v252
	v_exp_f32_e32 v253, v253
	v_add_f32_e32 v174, v238, v239
	v_add_f32_e32 v175, v240, v241
	v_add_f32_e32 v174, v174, v242
	v_add_f32_e32 v175, v175, v243
	v_add_f32_e32 v174, v174, v244
	v_add_f32_e32 v175, v175, v245
	v_add_f32_e32 v174, v174, v246
	v_add_f32_e32 v175, v175, v247
	v_add_f32_e32 v174, v174, v248
	v_add_f32_e32 v175, v175, v249
	v_add_f32_e32 v174, v174, v250
	v_add_f32_e32 v175, v175, v251
	v_add_f32_e32 v174, v174, v252
	v_add_f32_e32 v175, v175, v253
	v_add_f32_e32 v174, v174, v175
	v_add_f32_e32 v165, v165, v174
	v_cvt_pk_bf16_f32 v156, v238, v239
	v_cvt_pk_bf16_f32 v157, v240, v241
	v_cvt_pk_bf16_f32 v158, v242, v243
	v_cvt_pk_bf16_f32 v159, v244, v245
	v_cvt_pk_bf16_f32 v152, v246, v247
	v_cvt_pk_bf16_f32 v153, v248, v249
	v_cvt_pk_bf16_f32 v154, v250, v251
	v_cvt_pk_bf16_f32 v155, v252, v253
	v_exp_f32_e32 v128, v128
	v_exp_f32_e32 v129, v129
	v_exp_f32_e32 v130, v130
	v_exp_f32_e32 v131, v131
	v_exp_f32_e32 v132, v132
	v_exp_f32_e32 v133, v133
	v_exp_f32_e32 v134, v134
	v_exp_f32_e32 v135, v135
	v_exp_f32_e32 v136, v136
	v_exp_f32_e32 v137, v137
	v_exp_f32_e32 v138, v138
	v_exp_f32_e32 v139, v139
	v_exp_f32_e32 v140, v140
	v_exp_f32_e32 v141, v141
	v_exp_f32_e32 v142, v142
	v_exp_f32_e32 v143, v143
	v_add_f32_e32 v174, v128, v129
	v_add_f32_e32 v175, v130, v131
	v_add_f32_e32 v174, v174, v132
	v_add_f32_e32 v175, v175, v133
	v_add_f32_e32 v174, v174, v134
	v_add_f32_e32 v175, v175, v135
	v_add_f32_e32 v174, v174, v136
	v_add_f32_e32 v175, v175, v137
	v_add_f32_e32 v174, v174, v138
	v_add_f32_e32 v175, v175, v139
	v_add_f32_e32 v174, v174, v140
	v_add_f32_e32 v175, v175, v141
	v_add_f32_e32 v174, v174, v142
	v_add_f32_e32 v175, v175, v143
	v_add_f32_e32 v174, v174, v175
	v_add_f32_e32 v164, v164, v174
	v_cvt_pk_bf16_f32 v135, v134, v135
	v_cvt_pk_bf16_f32 v134, v132, v133
	v_cvt_pk_bf16_f32 v133, v130, v131
	v_cvt_pk_bf16_f32 v132, v128, v129
	v_cvt_pk_bf16_f32 v128, v136, v137
	v_cvt_pk_bf16_f32 v129, v138, v139
	v_cvt_pk_bf16_f32 v130, v140, v141
	v_cvt_pk_bf16_f32 v131, v142, v143
	s_nop 1
	s_waitcnt lgkmcnt(1)
	v_mfma_f32_32x32x16_bf16 v[112:127], v[228:231], v[156:159], v[112:127]
	v_mfma_f32_32x32x16_bf16 v[96:111], v[228:231], v[132:135], v[96:111]
	ds_read_b128 v[228:231], v217 offset:9280
	s_waitcnt lgkmcnt(1)
; #define LAS __attribute__((address_space(3)))
; #define SB0() __builtin_amdgcn_sched_barrier(0)
; template <bool SHIFT> DI void attn_unit(LAS unsigned char* lds, const bf16_t* Qb, const bf16_t* Kb, const bf16_t* Vt, bf16_t* concat,
;                   int b, int h, int qt, float shift2, float lam, int lam_init_bits, const float* subln_g) {
;     ...
;     const bool lag = wid >= 4;
;     bf16x8 Pc[2][2];
; #pragma unroll
;     for (int m = 0; m < 2; ++m)
; #pragma unroll
;         for (int g = 0; g < 2; ++g) { u32x4 z = {0u, 0u, 0u, 0u}; Pc[m][g] = __builtin_bit_cast(bf16x8, z); }
;     const LAS unsigned char* vold = lds + V_OFF + r * VP + hh * 16;
;     int vcur = 0;
;     for (int kt = 0; kt < nkt; ++kt) {
;         const int cur = kt & 1, nx = cur ^ 1;
;         const int vnx = vcur == 2 ? 0 : vcur + 1;
;         const bool pf = (kt + 1 < nkt);
;         const size_t ko = (size_t)(kt + 1) * 64;
;         if (pf) { *(LAS u32x4*)(lds + K_OFF + nx * K_BYTES + krow0 * QP + kc * 16) = sg0; *(LAS u32x4*)(lds + K_OFF + nx * K_BYTES + (krow0 + 32) * QP + kc * 16) = sg1;
;             sg0 = *(const u32x4*)(vg + (size_t)(vrow0) * TPB + ko + vc * 8); sg1 = *(const u32x4*)(vg + (size_t)(vrow0 + 64) * TPB + ko + vc * 8); }
;         const LAS unsigned char* kb = lds + K_OFF + cur * K_BYTES + r * QP + hh * 16;
;         const LAS unsigned char* vb = lds + V_OFF + vcur * V_BYTES + r * VP + hh * 16;
; #pragma unroll
;         for (int half = 0; half < 2; ++half) {
;             if (lag) PVH(Pc, vold);
;             QKEXP(Pc, half);
;             if (half == 0 && pf) { *(LAS u32x4*)(lds + V_OFF + vnx * V_BYTES + vrow0 * VP + vc * 16) = sg0; *(LAS u32x4*)(lds + V_OFF + vnx * V_BYTES + (vrow0 + 64) * VP + vc * 16) = sg1;
;                 if (kt + 2 < nkt) { sg0 = *(const u32x4*)(kg + (ko + 64 + krow0) * 1024 + kc * 8); sg1 = *(const u32x4*)(kg + (ko + 64 + krow0 + 32) * 1024 + kc * 8); } }
;             vold = vb + half * 64;
;             SB0();
;             if (!lag) PVH(Pc, vold);
	v_mfma_f32_32x32x16_bf16 v[80:95], v[232:235], v[156:159], v[80:95]
	v_mfma_f32_32x32x16_bf16 v[64:79], v[232:235], v[132:135], v[64:79]
	ds_read_b128 v[232:235], v217 offset:13888
	s_waitcnt lgkmcnt(1)
	v_mfma_f32_32x32x16_bf16 v[32:47], v[228:231], v[156:159], v[32:47]
	v_mfma_f32_32x32x16_bf16 v[48:63], v[228:231], v[132:135], v[48:63]
	ds_read_b128 v[228:231], v217 offset:96
	s_waitcnt lgkmcnt(1)
	v_mfma_f32_32x32x16_bf16 v[16:31], v[232:235], v[156:159], v[16:31]
	v_mfma_f32_32x32x16_bf16 v[0:15], v[232:235], v[132:135], v[0:15]
	ds_read_b128 v[232:235], v217 offset:4704
	s_waitcnt lgkmcnt(1)
	v_mfma_f32_32x32x16_bf16 v[112:127], v[228:231], v[152:155], v[112:127]
	v_mfma_f32_32x32x16_bf16 v[96:111], v[228:231], v[128:131], v[96:111]
	ds_read_b128 v[228:231], v217 offset:9312
	s_waitcnt lgkmcnt(1)
	v_mfma_f32_32x32x16_bf16 v[80:95], v[232:235], v[152:155], v[80:95]
	v_mfma_f32_32x32x16_bf16 v[64:79], v[232:235], v[128:131], v[64:79]
	ds_read_b128 v[232:235], v217 offset:13920
	s_waitcnt lgkmcnt(1)
	v_mfma_f32_32x32x16_bf16 v[32:47], v[228:231], v[152:155], v[32:47]
	v_mfma_f32_32x32x16_bf16 v[48:63], v[228:231], v[128:131], v[48:63]
	s_waitcnt lgkmcnt(0)
	v_mfma_f32_32x32x16_bf16 v[16:31], v[232:235], v[152:155], v[16:31]
	v_mfma_f32_32x32x16_bf16 v[0:15], v[232:235], v[128:131], v[0:15]
	s_waitcnt lgkmcnt(0)
	s_branch .Lattn_tile_end
.Lattn_lag:
	ds_read_b128 v[228:231], v136
	ds_read_b128 v[232:235], v136 offset:4608
	s_waitcnt lgkmcnt(1)
	v_mfma_f32_32x32x16_bf16 v[112:127], v[228:231], v[156:159], v[112:127]
	v_mfma_f32_32x32x16_bf16 v[96:111], v[228:231], v[132:135], v[96:111]
	ds_read_b128 v[228:231], v136 offset:9216
	s_waitcnt lgkmcnt(1)
	v_mfma_f32_32x32x16_bf16 v[80:95], v[232:235], v[156:159], v[80:95]
	v_mfma_f32_32x32x16_bf16 v[64:79], v[232:235], v[132:135], v[64:79]
	ds_read_b128 v[232:235], v136 offset:13824
	s_waitcnt lgkmcnt(1)
	v_mfma_f32_32x32x16_bf16 v[32:47], v[228:231], v[156:159], v[32:47]
	v_mfma_f32_32x32x16_bf16 v[48:63], v[228:231], v[132:135], v[48:63]
	ds_read_b128 v[228:231], v136 offset:32
	s_waitcnt lgkmcnt(1)
	v_mfma_f32_32x32x16_bf16 v[16:31], v[232:235], v[156:159], v[16:31]
	v_mfma_f32_32x32x16_bf16 v[0:15], v[232:235], v[132:135], v[0:15]
	ds_read_b128 v[232:235], v136 offset:4640
	s_waitcnt lgkmcnt(1)
	v_mfma_f32_32x32x16_bf16 v[112:127], v[228:231], v[152:155], v[112:127]
	v_mfma_f32_32x32x16_bf16 v[96:111], v[228:231], v[128:131], v[96:111]
	ds_read_b128 v[228:231], v136 offset:9248
	s_waitcnt lgkmcnt(1)
	v_mfma_f32_32x32x16_bf16 v[80:95], v[232:235], v[152:155], v[80:95]
	v_mfma_f32_32x32x16_bf16 v[64:79], v[232:235], v[128:131], v[64:79]
	ds_read_b128 v[232:235], v136 offset:13856
	ds_read_b128 v[178:181], v254
	ds_read_b128 v[194:197], v211
	ds_read_b128 v[182:185], v254 offset:32
	ds_read_b128 v[198:201], v211 offset:32
	ds_read_b128 v[186:189], v254 offset:64
	ds_read_b128 v[202:205], v211 offset:64
	ds_read_b128 v[190:193], v254 offset:96
	ds_read_b128 v[206:209], v211 offset:96
	s_waitcnt lgkmcnt(9)
	v_mfma_f32_32x32x16_bf16 v[32:47], v[228:231], v[152:155], v[32:47]
	v_mfma_f32_32x32x16_bf16 v[48:63], v[228:231], v[128:131], v[48:63]
	s_waitcnt lgkmcnt(8)
	v_mfma_f32_32x32x16_bf16 v[16:31], v[232:235], v[152:155], v[16:31]
	v_mfma_f32_32x32x16_bf16 v[0:15], v[232:235], v[128:131], v[0:15]
	s_waitcnt lgkmcnt(6)
	v_mfma_f32_32x32x16_bf16 v[238:253], v[178:181], v[194:197], 0
	ds_read_b128 v[178:181], v254 offset:128
	ds_read_b128 v[194:197], v211 offset:128
	s_waitcnt lgkmcnt(6)
	v_mfma_f32_32x32x16_bf16 v[238:253], v[182:185], v[198:201], v[238:253]
	ds_read_b128 v[182:185], v254 offset:160
	ds_read_b128 v[198:201], v211 offset:160
	s_waitcnt lgkmcnt(6)
	v_mfma_f32_32x32x16_bf16 v[238:253], v[186:189], v[202:205], v[238:253]
	ds_read_b128 v[186:189], v254 offset:192
	ds_read_b128 v[202:205], v211 offset:192
	s_waitcnt lgkmcnt(6)
	v_mfma_f32_32x32x16_bf16 v[238:253], v[190:193], v[206:209], v[238:253]
	ds_read_b128 v[190:193], v254 offset:224
	ds_read_b128 v[206:209], v211 offset:224
	s_waitcnt lgkmcnt(6)
	v_mfma_f32_32x32x16_bf16 v[128:143], v[178:181], v[194:197], 0
	s_waitcnt lgkmcnt(4)
	v_mfma_f32_32x32x16_bf16 v[128:143], v[182:185], v[198:201], v[128:143]
	s_waitcnt lgkmcnt(2)
	v_mfma_f32_32x32x16_bf16 v[128:143], v[186:189], v[202:205], v[128:143]
	s_waitcnt lgkmcnt(0)
	v_mfma_f32_32x32x16_bf16 v[128:143], v[190:193], v[206:209], v[128:143]
	ds_read_b128 v[228:231], v217
	ds_read_b128 v[232:235], v217 offset:4608
	s_nop 3
	v_exp_f32_e32 v238, v238
	v_exp_f32_e32 v239, v239
	v_exp_f32_e32 v240, v240
	v_exp_f32_e32 v241, v241
	v_exp_f32_e32 v242, v242
	v_exp_f32_e32 v243, v243
	v_exp_f32_e32 v244, v244
	v_exp_f32_e32 v245, v245
	v_exp_f32_e32 v246, v246
	v_exp_f32_e32 v247, v247
	v_exp_f32_e32 v248, v248
	v_exp_f32_e32 v249, v249
	v_exp_f32_e32 v250, v250
	v_exp_f32_e32 v251, v251
	v_exp_f32_e32 v252, v252
	v_exp_f32_e32 v253, v253
	v_add_f32_e32 v174, v238, v239
	v_add_f32_e32 v175, v240, v241
	v_add_f32_e32 v174, v174, v242
	v_add_f32_e32 v175, v175, v243
	v_add_f32_e32 v174, v174, v244
	v_add_f32_e32 v175, v175, v245
	v_add_f32_e32 v174, v174, v246
	v_add_f32_e32 v175, v175, v247
	v_add_f32_e32 v174, v174, v248
	v_add_f32_e32 v175, v175, v249
	v_add_f32_e32 v174, v174, v250
	v_add_f32_e32 v175, v175, v251
	v_add_f32_e32 v174, v174, v252
	v_add_f32_e32 v175, v175, v253
	v_add_f32_e32 v174, v174, v175
	v_add_f32_e32 v165, v165, v174
	v_cvt_pk_bf16_f32 v156, v238, v239
	v_cvt_pk_bf16_f32 v157, v240, v241
	v_cvt_pk_bf16_f32 v158, v242, v243
	v_cvt_pk_bf16_f32 v159, v244, v245
	v_cvt_pk_bf16_f32 v152, v246, v247
	v_cvt_pk_bf16_f32 v153, v248, v249
	v_cvt_pk_bf16_f32 v154, v250, v251
	v_cvt_pk_bf16_f32 v155, v252, v253
	v_exp_f32_e32 v128, v128
	v_exp_f32_e32 v129, v129
	v_exp_f32_e32 v130, v130
	v_exp_f32_e32 v131, v131
	v_exp_f32_e32 v132, v132
	v_exp_f32_e32 v133, v133
	v_exp_f32_e32 v134, v134
	v_exp_f32_e32 v135, v135
	v_exp_f32_e32 v136, v136
	v_exp_f32_e32 v137, v137
	v_exp_f32_e32 v138, v138
	v_exp_f32_e32 v139, v139
	v_exp_f32_e32 v140, v140
	v_exp_f32_e32 v141, v141
	v_exp_f32_e32 v142, v142
	v_exp_f32_e32 v143, v143
	v_add_f32_e32 v174, v128, v129
	v_add_f32_e32 v175, v130, v131
	v_add_f32_e32 v174, v174, v132
	v_add_f32_e32 v175, v175, v133
	v_add_f32_e32 v174, v174, v134
	v_add_f32_e32 v175, v175, v135
	v_add_f32_e32 v174, v174, v136
	v_add_f32_e32 v175, v175, v137
	v_add_f32_e32 v174, v174, v138
	v_add_f32_e32 v175, v175, v139
	v_add_f32_e32 v174, v174, v140
	v_add_f32_e32 v175, v175, v141
	v_add_f32_e32 v174, v174, v142
	v_add_f32_e32 v175, v175, v143
	v_add_f32_e32 v174, v174, v175
	v_add_f32_e32 v164, v164, v174
	v_cvt_pk_bf16_f32 v135, v134, v135
	v_cvt_pk_bf16_f32 v134, v132, v133
	v_cvt_pk_bf16_f32 v133, v130, v131
	v_cvt_pk_bf16_f32 v132, v128, v129
	v_cvt_pk_bf16_f32 v128, v136, v137
	v_cvt_pk_bf16_f32 v129, v138, v139
	v_cvt_pk_bf16_f32 v130, v140, v141
	v_cvt_pk_bf16_f32 v131, v142, v143
	s_nop 1
	s_waitcnt vmcnt(0)
	ds_write_b128 v218, v[144:147]
	ds_write_b128 v219, v[148:151]
	s_cmp_ge_u32 s34, s35
	s_cbranch_scc1 .Lattn_kskip_l
; #define LAS __attribute__((address_space(3)))
; #define SB0() __builtin_amdgcn_sched_barrier(0)
; template <bool SHIFT> DI void attn_unit(LAS unsigned char* lds, const bf16_t* Qb, const bf16_t* Kb, const bf16_t* Vt, bf16_t* concat,
;                   int b, int h, int qt, float shift2, float lam, int lam_init_bits, const float* subln_g) {
;     ...
;     const bool lag = wid >= 4;
;     bf16x8 Pc[2][2];
; #pragma unroll
;     for (int m = 0; m < 2; ++m)
; #pragma unroll
;         for (int g = 0; g < 2; ++g) { u32x4 z = {0u, 0u, 0u, 0u}; Pc[m][g] = __builtin_bit_cast(bf16x8, z); }
;     const LAS unsigned char* vold = lds + V_OFF + r * VP + hh * 16;
;     int vcur = 0;
;     for (int kt = 0; kt < nkt; ++kt) {
;         const int cur = kt & 1, nx = cur ^ 1;
;         const int vnx = vcur == 2 ? 0 : vcur + 1;
;         const bool pf = (kt + 1 < nkt);
;         const size_t ko = (size_t)(kt + 1) * 64;
;         if (pf) { *(LAS u32x4*)(lds + K_OFF + nx * K_BYTES + krow0 * QP + kc * 16) = sg0; *(LAS u32x4*)(lds + K_OFF + nx * K_BYTES + (krow0 + 32) * QP + kc * 16) = sg1;
;             sg0 = *(const u32x4*)(vg + (size_t)(vrow0) * TPB + ko + vc * 8); sg1 = *(const u32x4*)(vg + (size_t)(vrow0 + 64) * TPB + ko + vc * 8); }
;         const LAS unsigned char* kb = lds + K_OFF + cur * K_BYTES + r * QP + hh * 16;
;         const LAS unsigned char* vb = lds + V_OFF + vcur * V_BYTES + r * VP + hh * 16;
; #pragma unroll
;         for (int half = 0; half < 2; ++half) {
;             if (lag) PVH(Pc, vold);
;             QKEXP(Pc, half);
;             if (half == 0 && pf) { *(LAS u32x4*)(lds + V_OFF + vnx * V_BYTES + vrow0 * VP + vc * 16) = sg0; *(LAS u32x4*)(lds + V_OFF + vnx * V_BYTES + (vrow0 + 64) * VP + vc * 16) = sg1;
;                 if (kt + 2 < nkt) { sg0 = *(const u32x4*)(kg + (ko + 64 + krow0) * 1024 + kc * 8); sg1 = *(const u32x4*)(kg + (ko + 64 + krow0 + 32) * 1024 + kc * 8); } }
;             vold = vb + half * 64;
;             SB0();
;             if (!lag) PVH(Pc, vold);
;         }
;         __syncthreads();
;         vcur = vnx;
;     }
;     if (lag) PVH(Pc, vold);
	v_lshl_add_u64 v[170:171], v[166:167], 0, s[22:23]
	v_add_co_u32_e32 v172, vcc, 0xc5c8000, v170
	s_nop 1
	v_addc_co_u32_e32 v173, vcc, 0, v171, vcc
	v_add_co_u32_e32 v170, vcc, 0xc5d8000, v170
	s_nop 1
	v_addc_co_u32_e32 v171, vcc, 0, v171, vcc
	global_load_dwordx4 v[144:147], v[172:173], off
	global_load_dwordx4 v[148:151], v[170:171], off
.Lattn_kskip_l:
	s_waitcnt lgkmcnt(3)
	v_mfma_f32_32x32x16_bf16 v[112:127], v[228:231], v[156:159], v[112:127]
	v_mfma_f32_32x32x16_bf16 v[96:111], v[228:231], v[132:135], v[96:111]
	ds_read_b128 v[228:231], v217 offset:9216
	s_waitcnt lgkmcnt(3)
	v_mfma_f32_32x32x16_bf16 v[80:95], v[232:235], v[156:159], v[80:95]
	v_mfma_f32_32x32x16_bf16 v[64:79], v[232:235], v[132:135], v[64:79]
	ds_read_b128 v[232:235], v217 offset:13824
	s_waitcnt lgkmcnt(1)
	v_mfma_f32_32x32x16_bf16 v[32:47], v[228:231], v[156:159], v[32:47]
	v_mfma_f32_32x32x16_bf16 v[48:63], v[228:231], v[132:135], v[48:63]
	ds_read_b128 v[228:231], v217 offset:32
	s_waitcnt lgkmcnt(1)
	v_mfma_f32_32x32x16_bf16 v[16:31], v[232:235], v[156:159], v[16:31]
	v_mfma_f32_32x32x16_bf16 v[0:15], v[232:235], v[132:135], v[0:15]
	ds_read_b128 v[232:235], v217 offset:4640
	s_waitcnt lgkmcnt(1)
	v_mfma_f32_32x32x16_bf16 v[112:127], v[228:231], v[152:155], v[112:127]
	v_mfma_f32_32x32x16_bf16 v[96:111], v[228:231], v[128:131], v[96:111]
	ds_read_b128 v[228:231], v217 offset:9248
	s_waitcnt lgkmcnt(1)
	v_mfma_f32_32x32x16_bf16 v[80:95], v[232:235], v[152:155], v[80:95]
	v_mfma_f32_32x32x16_bf16 v[64:79], v[232:235], v[128:131], v[64:79]
	ds_read_b128 v[232:235], v217 offset:13856
	ds_read_b128 v[178:181], v254 offset:8704
	ds_read_b128 v[194:197], v211
	ds_read_b128 v[182:185], v254 offset:8736
	ds_read_b128 v[198:201], v211 offset:32
	ds_read_b128 v[186:189], v254 offset:8768
	ds_read_b128 v[202:205], v211 offset:64
	ds_read_b128 v[190:193], v254 offset:8800
	ds_read_b128 v[206:209], v211 offset:96
	s_waitcnt lgkmcnt(9)
	v_mfma_f32_32x32x16_bf16 v[32:47], v[228:231], v[152:155], v[32:47]
	v_mfma_f32_32x32x16_bf16 v[48:63], v[228:231], v[128:131], v[48:63]
	s_waitcnt lgkmcnt(8)
	v_mfma_f32_32x32x16_bf16 v[16:31], v[232:235], v[152:155], v[16:31]
	v_mfma_f32_32x32x16_bf16 v[0:15], v[232:235], v[128:131], v[0:15]
	s_waitcnt lgkmcnt(6)
	v_mfma_f32_32x32x16_bf16 v[238:253], v[178:181], v[194:197], 0
	ds_read_b128 v[178:181], v254 offset:8832
	ds_read_b128 v[194:197], v211 offset:128
	s_waitcnt lgkmcnt(6)
	v_mfma_f32_32x32x16_bf16 v[238:253], v[182:185], v[198:201], v[238:253]
	ds_read_b128 v[182:185], v254 offset:8864
	ds_read_b128 v[198:201], v211 offset:160
	s_waitcnt lgkmcnt(6)
	v_mfma_f32_32x32x16_bf16 v[238:253], v[186:189], v[202:205], v[238:253]
	ds_read_b128 v[186:189], v254 offset:8896
	ds_read_b128 v[202:205], v211 offset:192
	s_waitcnt lgkmcnt(6)
	v_mfma_f32_32x32x16_bf16 v[238:253], v[190:193], v[206:209], v[238:253]
	ds_read_b128 v[190:193], v254 offset:8928
	ds_read_b128 v[206:209], v211 offset:224
	s_waitcnt lgkmcnt(6)
	v_mfma_f32_32x32x16_bf16 v[128:143], v[178:181], v[194:197], 0
	s_waitcnt lgkmcnt(4)
	v_mfma_f32_32x32x16_bf16 v[128:143], v[182:185], v[198:201], v[128:143]
	s_waitcnt lgkmcnt(2)
	v_mfma_f32_32x32x16_bf16 v[128:143], v[186:189], v[202:205], v[128:143]
	s_waitcnt lgkmcnt(0)
	v_mfma_f32_32x32x16_bf16 v[128:143], v[190:193], v[206:209], v[128:143]
	s_nop 3
	v_exp_f32_e32 v238, v238
	v_exp_f32_e32 v239, v239
	v_exp_f32_e32 v240, v240
	v_exp_f32_e32 v241, v241
	v_exp_f32_e32 v242, v242
	v_exp_f32_e32 v243, v243
	v_exp_f32_e32 v244, v244
	v_exp_f32_e32 v245, v245
	v_exp_f32_e32 v246, v246
	v_exp_f32_e32 v247, v247
	v_exp_f32_e32 v248, v248
	v_exp_f32_e32 v249, v249
	v_exp_f32_e32 v250, v250
	v_exp_f32_e32 v251, v251
	v_exp_f32_e32 v252, v252
	v_exp_f32_e32 v253, v253
	v_add_f32_e32 v174, v238, v239
	v_add_f32_e32 v175, v240, v241
	v_add_f32_e32 v174, v174, v242
	v_add_f32_e32 v175, v175, v243
	v_add_f32_e32 v174, v174, v244
	v_add_f32_e32 v175, v175, v245
	v_add_f32_e32 v174, v174, v246
	v_add_f32_e32 v175, v175, v247
	v_add_f32_e32 v174, v174, v248
	v_add_f32_e32 v175, v175, v249
	v_add_f32_e32 v174, v174, v250
	v_add_f32_e32 v175, v175, v251
	v_add_f32_e32 v174, v174, v252
	v_add_f32_e32 v175, v175, v253
	v_add_f32_e32 v174, v174, v175
	v_add_f32_e32 v165, v165, v174
	v_cvt_pk_bf16_f32 v156, v238, v239
	v_cvt_pk_bf16_f32 v157, v240, v241
	v_cvt_pk_bf16_f32 v158, v242, v243
	v_cvt_pk_bf16_f32 v159, v244, v245
	v_cvt_pk_bf16_f32 v152, v246, v247
	v_cvt_pk_bf16_f32 v153, v248, v249
	v_cvt_pk_bf16_f32 v154, v250, v251
	v_cvt_pk_bf16_f32 v155, v252, v253
	v_exp_f32_e32 v128, v128
	v_exp_f32_e32 v129, v129
	v_exp_f32_e32 v130, v130
	v_exp_f32_e32 v131, v131
	v_exp_f32_e32 v132, v132
	v_exp_f32_e32 v133, v133
	v_exp_f32_e32 v134, v134
	v_exp_f32_e32 v135, v135
	v_exp_f32_e32 v136, v136
	v_exp_f32_e32 v137, v137
	v_exp_f32_e32 v138, v138
	v_exp_f32_e32 v139, v139
	v_exp_f32_e32 v140, v140
	v_exp_f32_e32 v141, v141
	v_exp_f32_e32 v142, v142
	v_exp_f32_e32 v143, v143
	v_add_f32_e32 v174, v128, v129
	v_add_f32_e32 v175, v130, v131
	v_add_f32_e32 v174, v174, v132
	v_add_f32_e32 v175, v175, v133
	v_add_f32_e32 v174, v174, v134
	v_add_f32_e32 v175, v175, v135
	v_add_f32_e32 v174, v174, v136
	v_add_f32_e32 v175, v175, v137
	v_add_f32_e32 v174, v174, v138
	v_add_f32_e32 v175, v175, v139
	v_add_f32_e32 v174, v174, v140
	v_add_f32_e32 v175, v175, v141
	v_add_f32_e32 v174, v174, v142
	v_add_f32_e32 v175, v175, v143
	v_add_f32_e32 v174, v174, v175
	v_add_f32_e32 v164, v164, v174
	v_cvt_pk_bf16_f32 v135, v134, v135
	v_cvt_pk_bf16_f32 v134, v132, v133
	v_cvt_pk_bf16_f32 v133, v130, v131
	v_cvt_pk_bf16_f32 v132, v128, v129
	v_cvt_pk_bf16_f32 v128, v136, v137
	v_cvt_pk_bf16_f32 v129, v138, v139
	v_cvt_pk_bf16_f32 v130, v140, v141
	v_cvt_pk_bf16_f32 v131, v142, v143
	s_nop 1
	s_waitcnt lgkmcnt(0)
.Lattn_tile_end:
	s_add_u32 s22, s22, 0x20000
	s_addc_u32 s23, s23, 0
	s_add_i32 s34, s34, 1
	v_add_u32_e32 v136, 64, v217
	s_cmp_eq_u32 s36, s22
	v_lshl_add_u64 v[168:169], v[168:169], 0, s[56:57]
	s_barrier
	s_cbranch_scc1 .LBB0_545
	s_mov_b32 s40, s65
	s_branch .LBB0_533
